# convert unit order kt-fastest within each weight segment (adjacent WGs write adjacent k-pieces of the same dst rows)
# speedup vs baseline: 1.0031x; 1.0031x over previous
; __device__ __forceinline__ void cvt_decode(PP p, int tile, const float*& src  , int& ld, bf16_t*& dst, int& K, int& k0, int& n0, int n4) {
;     ...
;   if (tile < NT_WGU) {
;     const int li = tile / (32 * 88), r = tile % (32 * 88), kt = r / 88, ntile = r % 88;
;     K = D; k0 = kt * 64; n0 = ntile * 128; ld = DFF; dst = (bf16_t*)(ws + WS_WGU) + (size_t)li * 2 * DFF * D;
;     const int pn = n0 / 256, bj = (n0 / 128) & 1;
;     const float* base = (bj ? p->ffn_wu : p->ffn_wg) + (size_t)li * D * DFF;
;     src = base + (size_t)k0 * ld + pn * 128 + n4 * 4;
;   } else if (tile < NT_WGU + NT_WD) {
;     const int t2 = tile - NT_WGU; const int li = t2 / (88 * 16), r = t2 % (88 * 16), kt = r / 16, ntile = r % 16;
;     K = DFF; k0 = kt * 64; n0 = ntile * 128; ld = D; dst = (bf16_t*)(ws + WS_WD) + (size_t)li * D * DFF;
;     src = p->ffn_wd + (size_t)li * DFF * D + (size_t)k0 * ld + n0 + n4 * 4;
;   } else if (tile < NT_WGU + NT_WD + NT_WIN) {
;     const int t2 = tile - NT_WGU - NT_WD; const int l = t2 / (32 * 50), r = t2 % (32 * 50), kt = r / 50, ntile = r % 50;
;     K = D; k0 = kt * 64; n0 = ntile * 128; ld = DIN_SRC; dst = (bf16_t*)(ws + WS_WIN) + (size_t)l * DIN * D;
;     const int sc = win_src_col(n0 + n4 * 4);
;     if (sc >= 0) src = p->w_in + (size_t)l * D * DIN_SRC + (size_t)k0 * ld + sc;
;   } else {
;     const int t2 = tile - NT_WGU - NT_WD - NT_WIN; const int l = t2 / (32 * 16), r = t2 % (32 * 16), kt = r / 16, ntile = r % 16;
;     K = D; k0 = kt * 64; n0 = ntile * 128; ld = D; dst = (bf16_t*)(ws + WS_WOUT) + (size_t)l * D * D;
;     src = p->w_out + (size_t)l * D * D + (size_t)k0 * ld + n0 + n4 * 4;
;   }
.Lcvp_WD:
	s_load_dwordx2 s[6:7], s[4:5], 0x50
	s_mul_i32 s13, s3, 745
	s_lshr_b32 s13, s13, 15
	s_mul_i32 s12, s13, 44
	s_sub_u32 s12, s3, s12
	s_mul_i32 s14, s101, 0x2c00000
	s_lshl_b32 s15, s12, 20
	s_add_u32 s14, s14, s15
	s_lshl_b32 s15, s13, 10
	s_add_u32 s14, s14, s15
	s_mul_i32 s16, s101, 0x1600000
	s_add_u32 s16, s16, 0xb0bc000
	s_mul_i32 s15, s13, 0x2c0000
	s_add_u32 s16, s16, s15
	s_lshl_b32 s15, s12, 8
	s_add_u32 s16, s16, s15
	s_waitcnt lgkmcnt(0)
	s_add_u32 s6, s6, s14
	s_addc_u32 s7, s7, 0
	s_add_u32 s10, s8, s16
	s_addc_u32 s11, s9, 0
	v_lshlrev_b32_e32 v2, 16, v0
	v_lshl_add_u32 v2, v1, 4, v2
	v_mov_b32_e32 v3, 0
	v_lshl_add_u64 v[2:3], v[2:3], 0, s[6:7]
	v_mov_b32_e32 v4, 0x2000
	v_mov_b32_e32 v5, 0
	v_mul_u32_u24_e32 v156, 0xb000, v1
	v_lshl_add_u32 v156, v0, 4, v156
	v_mov_b32_e32 v157, 0
	v_lshl_add_u64 v[156:157], v[156:157], 0, s[10:11]
	v_mov_b32_e32 v158, 0x2c00
	v_mov_b32_e32 v159, 0
	s_branch .Lcvp_body
.Lcvp_WOUT:
	s_load_dwordx2 s[6:7], s[4:5], 0x60
	s_lshr_b32 s13, s3, 4
	s_and_b32 s12, s3, 15
	s_lshl_b32 s14, s101, 24
	s_lshl_b32 s15, s12, 20
	s_add_u32 s14, s14, s15
	s_lshl_b32 s15, s13, 10
	s_add_u32 s14, s14, s15
	s_lshl_b32 s16, s101, 23
	s_add_u32 s16, s16, 0x13abc000
	s_lshl_b32 s15, s13, 20
	s_add_u32 s16, s16, s15
	s_lshl_b32 s15, s12, 8
	s_add_u32 s16, s16, s15
	s_waitcnt lgkmcnt(0)
	s_add_u32 s6, s6, s14
	s_addc_u32 s7, s7, 0
	s_add_u32 s10, s8, s16
	s_addc_u32 s11, s9, 0
	v_lshlrev_b32_e32 v2, 16, v0
	v_lshl_add_u32 v2, v1, 4, v2
	v_mov_b32_e32 v3, 0
	v_lshl_add_u64 v[2:3], v[2:3], 0, s[6:7]
	v_mov_b32_e32 v4, 0x2000
	v_mov_b32_e32 v5, 0
	v_mul_u32_u24_e32 v156, 0x4000, v1
	v_lshl_add_u32 v156, v0, 4, v156
	v_mov_b32_e32 v157, 0
	v_lshl_add_u64 v[156:157], v[156:157], 0, s[10:11]
	v_mov_b32_e32 v158, 0x1000
	v_mov_b32_e32 v159, 0
	s_branch .Lcvp_body
.Lcvp_WIN:
	s_load_dwordx2 s[6:7], s[4:5], 0x58
	s_lshr_b32 s13, s3, 4
	s_and_b32 s12, s3, 15
	s_mul_i32 s14, s101, 0x3040000
	s_mul_i32 s15, s12, 0x304000
	s_add_u32 s14, s14, s15
	s_mul_i32 s16, s101, 0x1900000
	s_add_u32 s16, s16, 0x108bc000
	s_lshl_b32 s15, s13, 20
	s_add_u32 s16, s16, s15
	s_lshl_b32 s15, s12, 8
	s_add_u32 s16, s16, s15
	s_waitcnt lgkmcnt(0)
	s_add_u32 s6, s6, s14
	s_addc_u32 s7, s7, 0
	s_add_u32 s10, s8, s16
	s_addc_u32 s11, s9, 0
	s_lshl_b32 s15, s13, 8
	v_lshl_add_u32 v150, v1, 2, s15
	v_mov_b32_e32 v148, 0xfffff000
	v_mov_b32_e32 v149, 0xfffffa00
	v_mov_b32_e32 v147, 0
	v_cmp_le_u32_e32 vcc, 0x800, v150
	s_nop 1
	v_cndmask_b32_e64 v147, v147, 16, vcc
	v_cmp_le_u32_e32 vcc, 0x1200, v150
	s_nop 1
	v_cndmask_b32_e64 v147, v147, 32, vcc
	v_cmp_le_u32_e32 vcc, 0x1800, v150
	s_nop 1
	v_cndmask_b32_e32 v147, v147, v148, vcc
	v_cmp_le_u32_e32 vcc, 0x1810, v150
	s_nop 1
	v_cndmask_b32_e32 v147, v147, v149, vcc
	v_add_u32_e32 v147, v150, v147
	v_mul_u32_u24_e32 v2, 0x30400, v0
	v_lshl_add_u32 v2, v147, 2, v2
	v_mov_b32_e32 v3, 0
	v_lshl_add_u64 v[2:3], v[2:3], 0, s[6:7]
	v_mov_b32_e32 v4, 0x6080
	v_mov_b32_e32 v5, 0
	s_add_u32 s14, s8, 0x5000
	s_addc_u32 s15, s9, 0
	v_mov_b32_e32 v148, s14
	v_mov_b32_e32 v149, s15
	v_cmp_le_u32_e32 vcc, 0x1820, v150
	s_nop 1
	v_cndmask_b32_e32 v2, v2, v148, vcc
	v_cndmask_b32_e32 v3, v3, v149, vcc
	v_cndmask_b32_e64 v4, v4, 0, vcc
	v_mul_u32_u24_e32 v156, 0x4000, v1
	v_lshl_add_u32 v156, v0, 4, v156
	v_mov_b32_e32 v157, 0
	v_lshl_add_u64 v[156:157], v[156:157], 0, s[10:11]
	v_mov_b32_e32 v158, 0x1000
	v_mov_b32_e32 v159, 0
	s_branch .Lcvp_body
.Lcvp_WGU:
	s_load_dwordx2 s[6:7], s[4:5], 0x40
	s_load_dwordx2 s[0:1], s[4:5], 0x48
	s_lshr_b32 s13, s3, 4
	s_and_b32 s12, s3, 15
	s_mul_i32 s14, s101, 0x2c00000
	s_mul_i32 s15, s12, 0x2c0000
	s_add_u32 s14, s14, s15
	s_lshl_b32 s15, s13, 9
	s_add_u32 s14, s14, s15
	s_mul_i32 s16, s101, 0x2c00000
	s_add_u32 s16, s16, 0xbc000
	s_lshl_b32 s15, s13, 20
	s_add_u32 s16, s16, s15
	s_lshl_b32 s15, s12, 8
	s_add_u32 s16, s16, s15
	s_waitcnt lgkmcnt(0)
	s_add_u32 s6, s6, s14
	s_addc_u32 s7, s7, 0
	s_add_u32 s0, s0, s14
	s_addc_u32 s1, s1, 0
	s_add_u32 s10, s8, s16
	s_addc_u32 s11, s9, 0
	v_mov_b32_e32 v2, s6
	v_mov_b32_e32 v3, s7
	v_mov_b32_e32 v148, s0
	v_mov_b32_e32 v149, s1
	v_cmp_le_u32_e32 vcc, 32, v1
	s_nop 1
	v_cndmask_b32_e32 v2, v2, v148, vcc
	v_cndmask_b32_e32 v3, v3, v149, vcc
	v_and_b32_e32 v147, 31, v1
	v_mul_u32_u24_e32 v150, 0x2c000, v0
	v_lshl_add_u32 v150, v147, 4, v150
	v_mov_b32_e32 v151, 0
	v_lshl_add_u64 v[2:3], v[2:3], 0, v[150:151]
	v_mov_b32_e32 v4, 0x5800
	v_mov_b32_e32 v5, 0
	v_mul_u32_u24_e32 v156, 0x4000, v1
	v_lshl_add_u32 v156, v0, 4, v156
	v_mov_b32_e32 v157, 0
	v_lshl_add_u64 v[156:157], v[156:157], 0, s[10:11]
	v_mov_b32_e32 v158, 0x1000
	v_mov_b32_e32 v159, 0
